# all four GEMMs: no accumulator clearing; first K-iteration peeled with C = 0 in each accumulator's first MFMA
# speedup vs baseline: 1.0171x; 1.0096x over previous
; #define PG8_STAGE(bufoff, gbase, voff) do { _Pragma("unroll") for (int _i = 0; _i < 2; ++_i) \
;         __builtin_amdgcn_global_load_lds((const unsigned*)((const char*)(gbase) + (voff)[_i]), (PG8_LAS unsigned*)(lds + (bufoff) + ldsw + _i * 8192), 16, 0, 0); } while (0)
; #define PG8_STAGEA(bufoff, gbase, voff) do { _Pragma("unroll") for (int _i = 0; _i < 2; ++_i) \
;         __builtin_amdgcn_global_load_lds((const unsigned*)((const char*)(gbase) + (voff)[_i]), (PG8_LAS unsigned*)(lds + (bufoff) + ldsw + _i * 8192), 16, 0, A_AUX); } while (0)
; #define PG8_LDA(dst, b, h) do { _Pragma("unroll") for (int m = 0; m < 4; ++m) _Pragma("unroll") for (int k = 0; k < 2; ++k) dst[m][k] = *(const PG8_LAS bf16x8*)(lds + PG8_SA(b, h) + aoff + m * 2048 + k * 1024); } while (0)
; #define PG8_LDB(dst, b, h) do { _Pragma("unroll") for (int n = 0; n < 2; ++n) _Pragma("unroll") for (int k = 0; k < 2; ++k) dst[n][k] = *(const PG8_LAS bf16x8*)(lds + PG8_SB(b, h) + boff + n * 2048 + k * 1024); } while (0)
; #define PG8_MMA(ai, bj, At, Bt) do { __builtin_amdgcn_s_setprio(1); _Pragma("unroll") for (int m = 0; m < 4; ++m) _Pragma("unroll") for (int n = 0; n < 2; ++n) _Pragma("unroll") for (int k = 0; k < 2; ++k) \
;         acc[ai][bj][m][n] = __builtin_amdgcn_mfma_f32_16x16x32_bf16(Bt[n][k], At[m][k], acc[ai][bj][m][n], 0, 0, 0); __builtin_amdgcn_s_setprio(0); } while (0)
; #define PG8_WAIT_V(n) asm volatile("s_waitcnt vmcnt(" #n ")" ::: "memory")
; #define PG8_WAIT_L(n) asm volatile("s_waitcnt lgkmcnt(" #n ")" ::: "memory")
; #define PG8_BAR __builtin_amdgcn_s_barrier()
;     ...
; #pragma unroll
;     for (int a = 0; a < 2; ++a)
; #pragma unroll
;         for (int b = 0; b < 2; ++b)
; #pragma unroll
;             for (int m = 0; m < 4; ++m)
; #pragma unroll
;                 for (int n = 0; n < 2; ++n) acc[a][b][m][n] = (f32x4){0.f, 0.f, 0.f, 0.f};
;     ...
;             PG8_LDB(B0, 0, 0); PG8_LDB(B1, 0, 1); PG8_SCHED; PG8_LDA(At, 0, 0); PG8_STAGEA(PG8_SA(1, 1), a1 + hstep, voffA);
;             PG8_WAIT_V(8); PG8_WAIT_L(0); PG8_BAR; PG8_MMA(0, 0, At, B0); PG8_MMA(0, 1, At, B1); PG8_BAR; PG8_SCHED;
;             PG8_LDA(At, 0, 1); PG8_STAGE(PG8_SB(0, 0), b2, voffB); PG8_STAGE(PG8_SB(0, 1), b2 + hstep, voffB); PG8_STAGEA(PG8_SA(0, 0), a2, voffA);
;             PG8_WAIT_V(8); PG8_WAIT_L(0); PG8_BAR; PG8_MMA(1, 0, At, B0); PG8_MMA(1, 1, At, B1); PG8_BAR; PG8_SCHED;
.LBB0_185:
	s_ashr_i32 s53, s52, 31
	s_lshl_b64 s[16:17], s[52:53], 19
	s_add_u32 s54, s97, s16
	s_addc_u32 s55, s29, s17
	s_and_b64 s[16:17], s[38:39], exec
	s_cselect_b32 s16, s55, s1
	s_cselect_b32 s17, s54, s0
	s_ashr_i32 s51, s50, 31
	s_lshl_b64 s[42:43], s[50:51], 19
	v_readlane_b32 s51, v246, 9
	s_add_u32 s56, s51, s42
	v_readlane_b32 s42, v246, 6
	s_addc_u32 s57, s42, s43
	s_and_b64 s[42:43], s[38:39], exec
	s_cselect_b32 s51, s57, s41
	s_cselect_b32 s53, s56, s40
	s_add_u32 s0, s0, 0x40080
	s_addc_u32 s1, s1, 0
	s_add_u32 s58, s40, 0x100
	s_addc_u32 s59, s41, 0
	s_mov_b32 vcc_lo, -2
	s_add_u32 s40, s0, 0xfffc0080
	s_addc_u32 s41, s1, -1
	s_add_i32 s70, 0, 0x10000
	s_cmp_eq_u32 vcc_lo, 12
	s_cselect_b32 s43, s16, s41
	s_cselect_b32 s42, s17, s40
	s_cselect_b32 s41, s51, s59
	s_cselect_b32 s40, s53, s58
	s_add_i32 vcc_hi, 0, 0x14000
	v_add_u32_e32 v94, s70, v201
	v_add_u32_e32 v158, vcc_hi, v201
	ds_read_b128 v[74:77], v94
	ds_read_b128 v[78:81], v94 offset:1024
	ds_read_b128 v[90:93], v94 offset:2048
	ds_read_b128 v[94:97], v94 offset:3072
	ds_read_b128 v[146:149], v158
	ds_read_b128 v[150:153], v158 offset:1024
	ds_read_b128 v[154:157], v158 offset:2048
	ds_read_b128 v[158:161], v158 offset:3072
	v_lshl_add_u64 v[190:191], s[0:1], 0, v[182:183]
	s_add_i32 m0, s61, 0xc000
	ds_read_b128 v[186:189], v203
	ds_read_b128 v[208:211], v203 offset:1024
	ds_read_b128 v[212:215], v203 offset:2048
	ds_read_b128 v[216:219], v203 offset:3072
	ds_read_b128 v[220:223], v203 offset:4096
	ds_read_b128 v[224:227], v203 offset:5120
	ds_read_b128 v[228:231], v203 offset:6144
	ds_read_b128 v[232:235], v203 offset:7168
	global_load_lds_dwordx4 v[190:191], off
	v_lshl_add_u64 v[190:191], s[0:1], 0, v[184:185]
	s_add_i32 m0, s61, 0xe000
	s_nop 0
	global_load_lds_dwordx4 v[190:191], off
	s_waitcnt vmcnt(8)
	s_waitcnt lgkmcnt(0)
	s_barrier
	s_setprio 1
	s_waitcnt lgkmcnt(0)
	v_mfma_f32_16x16x32_bf16 v[142:145], v[74:77], v[186:189], 0
	v_mfma_f32_16x16x32_bf16 v[138:141], v[90:93], v[186:189], 0
	v_mfma_f32_16x16x32_bf16 v[126:129], v[74:77], v[212:215], 0
	v_mfma_f32_16x16x32_bf16 v[122:125], v[90:93], v[212:215], 0
	v_mfma_f32_16x16x32_bf16 v[110:113], v[74:77], v[220:223], 0
	v_mfma_f32_16x16x32_bf16 v[106:109], v[90:93], v[220:223], 0
	v_mfma_f32_16x16x32_bf16 v[86:89], v[74:77], v[228:231], 0
	v_mfma_f32_16x16x32_bf16 v[82:85], v[90:93], v[228:231], 0
	v_mfma_f32_16x16x32_bf16 v[142:145], v[78:81], v[208:211], v[142:145]
	v_mfma_f32_16x16x32_bf16 v[138:141], v[94:97], v[208:211], v[138:141]
	v_mfma_f32_16x16x32_bf16 v[126:129], v[78:81], v[216:219], v[126:129]
	v_mfma_f32_16x16x32_bf16 v[122:125], v[94:97], v[216:219], v[122:125]
	v_mfma_f32_16x16x32_bf16 v[110:113], v[78:81], v[224:227], v[110:113]
	v_mfma_f32_16x16x32_bf16 v[106:109], v[94:97], v[224:227], v[106:109]
	v_mfma_f32_16x16x32_bf16 v[86:89], v[78:81], v[232:235], v[86:89]
	v_mfma_f32_16x16x32_bf16 v[82:85], v[94:97], v[232:235], v[82:85]
	s_setprio 0
	s_setprio 1
	v_mfma_f32_16x16x32_bf16 v[134:137], v[146:149], v[186:189], 0
	v_mfma_f32_16x16x32_bf16 v[130:133], v[154:157], v[186:189], 0
	v_mfma_f32_16x16x32_bf16 v[118:121], v[146:149], v[212:215], 0
	v_mfma_f32_16x16x32_bf16 v[114:117], v[154:157], v[212:215], 0
	v_mfma_f32_16x16x32_bf16 v[102:105], v[146:149], v[220:223], 0
	v_mfma_f32_16x16x32_bf16 v[98:101], v[154:157], v[220:223], 0
	v_mfma_f32_16x16x32_bf16 v[70:73], v[146:149], v[228:231], 0
	v_mfma_f32_16x16x32_bf16 v[66:69], v[154:157], v[228:231], 0
	v_mfma_f32_16x16x32_bf16 v[134:137], v[150:153], v[208:211], v[134:137]
	v_mfma_f32_16x16x32_bf16 v[130:133], v[158:161], v[208:211], v[130:133]
	v_mfma_f32_16x16x32_bf16 v[118:121], v[150:153], v[216:219], v[118:121]
	v_mfma_f32_16x16x32_bf16 v[114:117], v[158:161], v[216:219], v[114:117]
	v_mfma_f32_16x16x32_bf16 v[102:105], v[150:153], v[224:227], v[102:105]
	v_mfma_f32_16x16x32_bf16 v[98:101], v[158:161], v[224:227], v[98:101]
	v_mfma_f32_16x16x32_bf16 v[70:73], v[150:153], v[232:235], v[70:73]
	v_mfma_f32_16x16x32_bf16 v[66:69], v[158:161], v[232:235], v[66:69]
	s_setprio 0
	s_barrier
	s_add_i32 s70, s70, s60
	v_lshl_add_u64 v[190:191], s[40:41], 0, v[0:1]
	s_mov_b32 m0, s70
	ds_read_b128 v[186:189], v203 offset:16384
	ds_read_b128 v[208:211], v203 offset:17408
	ds_read_b128 v[212:215], v203 offset:18432
	ds_read_b128 v[216:219], v203 offset:19456
	ds_read_b128 v[220:223], v203 offset:20480
	ds_read_b128 v[224:227], v203 offset:21504
	ds_read_b128 v[228:231], v203 offset:22528
	ds_read_b128 v[232:235], v203 offset:23552
	global_load_lds_dwordx4 v[190:191], off
	s_add_i32 m0, s70, 0x2000
	s_add_u32 s70, s40, 0x40000
	v_lshl_add_u64 v[236:237], s[40:41], 0, v[174:175]
	s_addc_u32 s71, s41, 0
	s_add_i32 vcc_hi, vcc_hi, s60
	global_load_lds_dwordx4 v[236:237], off
	v_lshl_add_u64 v[238:239], s[70:71], 0, v[0:1]
	s_mov_b32 m0, vcc_hi
	v_lshl_add_u64 v[240:241], s[42:43], 0, v[176:177]
	global_load_lds_dwordx4 v[238:239], off
	v_lshl_add_u64 v[238:239], s[70:71], 0, v[174:175]
	s_add_i32 m0, vcc_hi, 0x2000
	s_nop 0
	global_load_lds_dwordx4 v[238:239], off
	v_lshl_add_u64 v[238:239], s[42:43], 0, v[178:179]
	s_mov_b32 m0, s61
	s_nop 0
	global_load_lds_dwordx4 v[238:239], off
	s_mov_b32 m0, s62
	s_nop 0
	global_load_lds_dwordx4 v[240:241], off
	s_waitcnt vmcnt(8)
	s_waitcnt lgkmcnt(0)
	s_barrier
; #define PG8_STAGEA(bufoff, gbase, voff) do { _Pragma("unroll") for (int _i = 0; _i < 2; ++_i) \
;         __builtin_amdgcn_global_load_lds((const unsigned*)((const char*)(gbase) + (voff)[_i]), (PG8_LAS unsigned*)(lds + (bufoff) + ldsw + _i * 8192), 16, 0, A_AUX); } while (0)
; #define PG8_LDA(dst, b, h) do { _Pragma("unroll") for (int m = 0; m < 4; ++m) _Pragma("unroll") for (int k = 0; k < 2; ++k) dst[m][k] = *(const PG8_LAS bf16x8*)(lds + PG8_SA(b, h) + aoff + m * 2048 + k * 1024); } while (0)
; #define PG8_LDB(dst, b, h) do { _Pragma("unroll") for (int n = 0; n < 2; ++n) _Pragma("unroll") for (int k = 0; k < 2; ++k) dst[n][k] = *(const PG8_LAS bf16x8*)(lds + PG8_SB(b, h) + boff + n * 2048 + k * 1024); } while (0)
; #define PG8_MMA(ai, bj, At, Bt) do { __builtin_amdgcn_s_setprio(1); _Pragma("unroll") for (int m = 0; m < 4; ++m) _Pragma("unroll") for (int n = 0; n < 2; ++n) _Pragma("unroll") for (int k = 0; k < 2; ++k) \
;         acc[ai][bj][m][n] = __builtin_amdgcn_mfma_f32_16x16x32_bf16(Bt[n][k], At[m][k], acc[ai][bj][m][n], 0, 0, 0); __builtin_amdgcn_s_setprio(0); } while (0)
; #define PG8_WAIT_V(n) asm volatile("s_waitcnt vmcnt(" #n ")" ::: "memory")
; #define PG8_WAIT_L(n) asm volatile("s_waitcnt lgkmcnt(" #n ")" ::: "memory")
; #define PG8_BAR __builtin_amdgcn_s_barrier()
; #define PG8_SCHED __builtin_amdgcn_sched_barrier(0)
;     ...
;             PG8_WAIT_V(8); PG8_WAIT_L(0); PG8_BAR; PG8_MMA(1, 0, At, B0); PG8_MMA(1, 1, At, B1); PG8_BAR; PG8_SCHED;
;             PG8_LDB(B0, 1, 0); PG8_LDB(B1, 1, 1); PG8_SCHED; PG8_LDA(At, 1, 0); PG8_STAGEA(PG8_SA(0, 1), a2 + hstep, voffA);
;             PG8_WAIT_V(8); PG8_WAIT_L(0); PG8_BAR; PG8_MMA(0, 0, At, B0); PG8_MMA(0, 1, At, B1); PG8_BAR; PG8_SCHED;
	s_setprio 1
	s_waitcnt lgkmcnt(0)
	v_mfma_f32_16x16x32_bf16 v[62:65], v[74:77], v[186:189], 0
	v_mfma_f32_16x16x32_bf16 v[58:61], v[90:93], v[186:189], 0
	v_mfma_f32_16x16x32_bf16 v[46:49], v[74:77], v[212:215], 0
	v_mfma_f32_16x16x32_bf16 v[42:45], v[90:93], v[212:215], 0
	v_mfma_f32_16x16x32_bf16 v[30:33], v[74:77], v[220:223], 0
	v_mfma_f32_16x16x32_bf16 v[26:29], v[90:93], v[220:223], 0
	v_mfma_f32_16x16x32_bf16 v[14:17], v[74:77], v[228:231], 0
	v_mfma_f32_16x16x32_bf16 v[10:13], v[90:93], v[228:231], 0
	v_mfma_f32_16x16x32_bf16 v[62:65], v[78:81], v[208:211], v[62:65]
	v_mfma_f32_16x16x32_bf16 v[58:61], v[94:97], v[208:211], v[58:61]
	v_mfma_f32_16x16x32_bf16 v[46:49], v[78:81], v[216:219], v[46:49]
	v_mfma_f32_16x16x32_bf16 v[42:45], v[94:97], v[216:219], v[42:45]
	v_mfma_f32_16x16x32_bf16 v[30:33], v[78:81], v[224:227], v[30:33]
	v_mfma_f32_16x16x32_bf16 v[26:29], v[94:97], v[224:227], v[26:29]
	v_mfma_f32_16x16x32_bf16 v[14:17], v[78:81], v[232:235], v[14:17]
	v_mfma_f32_16x16x32_bf16 v[10:13], v[94:97], v[232:235], v[10:13]
	s_setprio 0
	s_setprio 1
	v_mfma_f32_16x16x32_bf16 v[54:57], v[146:149], v[186:189], 0
	v_mfma_f32_16x16x32_bf16 v[50:53], v[154:157], v[186:189], 0
	v_mfma_f32_16x16x32_bf16 v[38:41], v[146:149], v[212:215], 0
	v_mfma_f32_16x16x32_bf16 v[34:37], v[154:157], v[212:215], 0
	v_mfma_f32_16x16x32_bf16 v[22:25], v[146:149], v[220:223], 0
	v_mfma_f32_16x16x32_bf16 v[18:21], v[154:157], v[220:223], 0
	v_mfma_f32_16x16x32_bf16 v[6:9], v[146:149], v[228:231], 0
	v_mfma_f32_16x16x32_bf16 v[2:5], v[154:157], v[228:231], 0
	v_mfma_f32_16x16x32_bf16 v[54:57], v[150:153], v[208:211], v[54:57]
	v_mfma_f32_16x16x32_bf16 v[50:53], v[158:161], v[208:211], v[50:53]
	v_mfma_f32_16x16x32_bf16 v[38:41], v[150:153], v[216:219], v[38:41]
	v_mfma_f32_16x16x32_bf16 v[34:37], v[158:161], v[216:219], v[34:37]
	v_mfma_f32_16x16x32_bf16 v[22:25], v[150:153], v[224:227], v[22:25]
	v_mfma_f32_16x16x32_bf16 v[18:21], v[158:161], v[224:227], v[18:21]
	v_mfma_f32_16x16x32_bf16 v[6:9], v[150:153], v[232:235], v[6:9]
	v_mfma_f32_16x16x32_bf16 v[2:5], v[158:161], v[232:235], v[2:5]
	s_setprio 0
	s_barrier
	s_add_i32 s70, 0, 0x18000
	s_add_i32 s71, 0, 0x1c000
	v_add_u32_e32 v94, s70, v201
	v_add_u32_e32 v158, s71, v201
	ds_read_b128 v[74:77], v94
	ds_read_b128 v[78:81], v94 offset:1024
	ds_read_b128 v[90:93], v94 offset:2048
	ds_read_b128 v[94:97], v94 offset:3072
	ds_read_b128 v[146:149], v158
	ds_read_b128 v[150:153], v158 offset:1024
	ds_read_b128 v[154:157], v158 offset:2048
	ds_read_b128 v[158:161], v158 offset:3072
	s_add_u32 s42, s42, 0x40000
	s_addc_u32 s43, s43, 0
	s_mov_b32 m0, s63
	v_lshl_add_u64 v[242:243], s[42:43], 0, v[178:179]
	ds_read_b128 v[186:189], v203 offset:32768
	ds_read_b128 v[208:211], v203 offset:33792
	ds_read_b128 v[212:215], v203 offset:34816
	ds_read_b128 v[216:219], v203 offset:35840
	ds_read_b128 v[220:223], v203 offset:36864
	ds_read_b128 v[224:227], v203 offset:37888
	ds_read_b128 v[228:231], v203 offset:38912
	ds_read_b128 v[232:235], v203 offset:39936
	global_load_lds_dwordx4 v[242:243], off
	v_lshl_add_u64 v[242:243], s[42:43], 0, v[176:177]
	s_mov_b32 m0, s64
	s_nop 0
	global_load_lds_dwordx4 v[242:243], off
	s_waitcnt vmcnt(8)
	s_waitcnt lgkmcnt(0)
	s_barrier
	s_setprio 1
	s_waitcnt lgkmcnt(0)
	v_mfma_f32_16x16x32_bf16 v[142:145], v[74:77], v[186:189], v[142:145]
	v_mfma_f32_16x16x32_bf16 v[138:141], v[90:93], v[186:189], v[138:141]
	v_mfma_f32_16x16x32_bf16 v[126:129], v[74:77], v[212:215], v[126:129]
	v_mfma_f32_16x16x32_bf16 v[122:125], v[90:93], v[212:215], v[122:125]
	v_mfma_f32_16x16x32_bf16 v[110:113], v[74:77], v[220:223], v[110:113]
	v_mfma_f32_16x16x32_bf16 v[106:109], v[90:93], v[220:223], v[106:109]
	v_mfma_f32_16x16x32_bf16 v[86:89], v[74:77], v[228:231], v[86:89]
	v_mfma_f32_16x16x32_bf16 v[82:85], v[90:93], v[228:231], v[82:85]
	v_mfma_f32_16x16x32_bf16 v[142:145], v[78:81], v[208:211], v[142:145]
	v_mfma_f32_16x16x32_bf16 v[138:141], v[94:97], v[208:211], v[138:141]
	v_mfma_f32_16x16x32_bf16 v[126:129], v[78:81], v[216:219], v[126:129]
	v_mfma_f32_16x16x32_bf16 v[122:125], v[94:97], v[216:219], v[122:125]
	v_mfma_f32_16x16x32_bf16 v[110:113], v[78:81], v[224:227], v[110:113]
	v_mfma_f32_16x16x32_bf16 v[106:109], v[94:97], v[224:227], v[106:109]
	v_mfma_f32_16x16x32_bf16 v[86:89], v[78:81], v[232:235], v[86:89]
	v_mfma_f32_16x16x32_bf16 v[82:85], v[94:97], v[232:235], v[82:85]
	s_setprio 0
	s_setprio 1
	v_mfma_f32_16x16x32_bf16 v[134:137], v[146:149], v[186:189], v[134:137]
	v_mfma_f32_16x16x32_bf16 v[130:133], v[154:157], v[186:189], v[130:133]
	v_mfma_f32_16x16x32_bf16 v[118:121], v[146:149], v[212:215], v[118:121]
	v_mfma_f32_16x16x32_bf16 v[114:117], v[154:157], v[212:215], v[114:117]
	v_mfma_f32_16x16x32_bf16 v[102:105], v[146:149], v[220:223], v[102:105]
	v_mfma_f32_16x16x32_bf16 v[98:101], v[154:157], v[220:223], v[98:101]
	v_mfma_f32_16x16x32_bf16 v[70:73], v[146:149], v[228:231], v[70:73]
	v_mfma_f32_16x16x32_bf16 v[66:69], v[154:157], v[228:231], v[66:69]
	v_mfma_f32_16x16x32_bf16 v[134:137], v[150:153], v[208:211], v[134:137]
	v_mfma_f32_16x16x32_bf16 v[130:133], v[158:161], v[208:211], v[130:133]
	v_mfma_f32_16x16x32_bf16 v[118:121], v[150:153], v[216:219], v[118:121]
	v_mfma_f32_16x16x32_bf16 v[114:117], v[158:161], v[216:219], v[114:117]
	v_mfma_f32_16x16x32_bf16 v[102:105], v[150:153], v[224:227], v[102:105]
	v_mfma_f32_16x16x32_bf16 v[98:101], v[158:161], v[224:227], v[98:101]
	v_mfma_f32_16x16x32_bf16 v[70:73], v[150:153], v[232:235], v[70:73]
	v_mfma_f32_16x16x32_bf16 v[66:69], v[158:161], v[232:235], v[66:69]
	s_setprio 0
	s_barrier
; #define PG8_STAGE(bufoff, gbase, voff) do { _Pragma("unroll") for (int _i = 0; _i < 2; ++_i) \
;         __builtin_amdgcn_global_load_lds((const unsigned*)((const char*)(gbase) + (voff)[_i]), (PG8_LAS unsigned*)(lds + (bufoff) + ldsw + _i * 8192), 16, 0, 0); } while (0)
; #define PG8_STAGEA(bufoff, gbase, voff) do { _Pragma("unroll") for (int _i = 0; _i < 2; ++_i) \
;         __builtin_amdgcn_global_load_lds((const unsigned*)((const char*)(gbase) + (voff)[_i]), (PG8_LAS unsigned*)(lds + (bufoff) + ldsw + _i * 8192), 16, 0, A_AUX); } while (0)
; #define PG8_LDA(dst, b, h) do { _Pragma("unroll") for (int m = 0; m < 4; ++m) _Pragma("unroll") for (int k = 0; k < 2; ++k) dst[m][k] = *(const PG8_LAS bf16x8*)(lds + PG8_SA(b, h) + aoff + m * 2048 + k * 1024); } while (0)
; #define PG8_MMA(ai, bj, At, Bt) do { __builtin_amdgcn_s_setprio(1); _Pragma("unroll") for (int m = 0; m < 4; ++m) _Pragma("unroll") for (int n = 0; n < 2; ++n) _Pragma("unroll") for (int k = 0; k < 2; ++k) \
;         acc[ai][bj][m][n] = __builtin_amdgcn_mfma_f32_16x16x32_bf16(Bt[n][k], At[m][k], acc[ai][bj][m][n], 0, 0, 0); __builtin_amdgcn_s_setprio(0); } while (0)
; #define PG8_WAIT_V(n) asm volatile("s_waitcnt vmcnt(" #n ")" ::: "memory")
; #define PG8_WAIT_L(n) asm volatile("s_waitcnt lgkmcnt(" #n ")" ::: "memory")
; #define PG8_BAR __builtin_amdgcn_s_barrier()
; #define PG8_SCHED __builtin_amdgcn_sched_barrier(0)
;     ...
;         for (int t = 0; t < nt; t += 2) {
;     ...
;             PG8_LDA(At, 1, 1); PG8_STAGE(PG8_SB(1, 0), b3, voffB); PG8_STAGE(PG8_SB(1, 1), b3 + hstep, voffB); PG8_STAGEA(PG8_SA(1, 0), a3, voffA);
;             PG8_WAIT_V(8); PG8_WAIT_L(0); PG8_BAR; PG8_MMA(1, 0, At, B0); PG8_MMA(1, 1, At, B1); PG8_BAR; PG8_SCHED;
	s_add_i32 s42, s70, s60
	v_lshl_add_u64 v[190:191], v[190:191], 0, s[8:9]
	s_mov_b32 m0, s42
	ds_read_b128 v[186:189], v203 offset:49152
	ds_read_b128 v[208:211], v203 offset:50176
	ds_read_b128 v[212:215], v203 offset:51200
	ds_read_b128 v[216:219], v203 offset:52224
	ds_read_b128 v[220:223], v203 offset:53248
	ds_read_b128 v[224:227], v203 offset:54272
	ds_read_b128 v[228:231], v203 offset:55296
	ds_read_b128 v[232:235], v203 offset:56320
	global_load_lds_dwordx4 v[190:191], off
	s_add_i32 m0, s42, 0x2000
	s_add_u32 s40, s40, 0x40080
	v_lshl_add_u64 v[190:191], v[236:237], 0, s[8:9]
	s_addc_u32 s41, s41, 0
	s_add_i32 s42, s71, s60
	global_load_lds_dwordx4 v[190:191], off
	v_lshl_add_u64 v[190:191], s[40:41], 0, v[0:1]
	s_mov_b32 m0, s42
	s_nop 0
	global_load_lds_dwordx4 v[190:191], off
	v_lshl_add_u64 v[190:191], s[40:41], 0, v[174:175]
	s_add_i32 m0, s42, 0x2000
	s_nop 0
	global_load_lds_dwordx4 v[190:191], off
	v_lshl_add_u64 v[190:191], v[238:239], 0, s[8:9]
	s_mov_b32 m0, s72
	s_nop 0
	global_load_lds_dwordx4 v[190:191], off
	v_lshl_add_u64 v[190:191], v[240:241], 0, s[8:9]
	s_mov_b32 m0, s73
	s_nop 0
	global_load_lds_dwordx4 v[190:191], off
	s_waitcnt vmcnt(8)
	s_waitcnt lgkmcnt(0)
	s_barrier
	s_setprio 1
	s_waitcnt lgkmcnt(0)
	v_mfma_f32_16x16x32_bf16 v[62:65], v[74:77], v[186:189], v[62:65]
	v_mfma_f32_16x16x32_bf16 v[58:61], v[90:93], v[186:189], v[58:61]
	v_mfma_f32_16x16x32_bf16 v[46:49], v[74:77], v[212:215], v[46:49]
	v_mfma_f32_16x16x32_bf16 v[42:45], v[90:93], v[212:215], v[42:45]
	v_mfma_f32_16x16x32_bf16 v[30:33], v[74:77], v[220:223], v[30:33]
	v_mfma_f32_16x16x32_bf16 v[26:29], v[90:93], v[220:223], v[26:29]
	v_mfma_f32_16x16x32_bf16 v[14:17], v[74:77], v[228:231], v[14:17]
	v_mfma_f32_16x16x32_bf16 v[10:13], v[90:93], v[228:231], v[10:13]
	v_mfma_f32_16x16x32_bf16 v[62:65], v[78:81], v[208:211], v[62:65]
	v_mfma_f32_16x16x32_bf16 v[58:61], v[94:97], v[208:211], v[58:61]
	v_mfma_f32_16x16x32_bf16 v[46:49], v[78:81], v[216:219], v[46:49]
	v_mfma_f32_16x16x32_bf16 v[42:45], v[94:97], v[216:219], v[42:45]
	v_mfma_f32_16x16x32_bf16 v[30:33], v[78:81], v[224:227], v[30:33]
	v_mfma_f32_16x16x32_bf16 v[26:29], v[94:97], v[224:227], v[26:29]
	v_mfma_f32_16x16x32_bf16 v[14:17], v[78:81], v[232:235], v[14:17]
	v_mfma_f32_16x16x32_bf16 v[10:13], v[94:97], v[232:235], v[10:13]
	s_setprio 0
	s_setprio 1
	v_mfma_f32_16x16x32_bf16 v[54:57], v[146:149], v[186:189], v[54:57]
	v_mfma_f32_16x16x32_bf16 v[50:53], v[154:157], v[186:189], v[50:53]
	v_mfma_f32_16x16x32_bf16 v[38:41], v[146:149], v[212:215], v[38:41]
	v_mfma_f32_16x16x32_bf16 v[34:37], v[154:157], v[212:215], v[34:37]
	v_mfma_f32_16x16x32_bf16 v[22:25], v[146:149], v[220:223], v[22:25]
	v_mfma_f32_16x16x32_bf16 v[18:21], v[154:157], v[220:223], v[18:21]
	v_mfma_f32_16x16x32_bf16 v[6:9], v[146:149], v[228:231], v[6:9]
	v_mfma_f32_16x16x32_bf16 v[2:5], v[154:157], v[228:231], v[2:5]
	v_mfma_f32_16x16x32_bf16 v[54:57], v[150:153], v[208:211], v[54:57]
	v_mfma_f32_16x16x32_bf16 v[50:53], v[158:161], v[208:211], v[50:53]
	v_mfma_f32_16x16x32_bf16 v[38:41], v[150:153], v[216:219], v[38:41]
	v_mfma_f32_16x16x32_bf16 v[34:37], v[158:161], v[216:219], v[34:37]
	v_mfma_f32_16x16x32_bf16 v[22:25], v[150:153], v[224:227], v[22:25]
	v_mfma_f32_16x16x32_bf16 v[18:21], v[158:161], v[224:227], v[18:21]
	v_mfma_f32_16x16x32_bf16 v[6:9], v[150:153], v[232:235], v[6:9]
	v_mfma_f32_16x16x32_bf16 v[2:5], v[158:161], v[232:235], v[2:5]
	s_setprio 0
	s_barrier
	s_add_i32 vcc_lo, vcc_lo, 2
	s_add_u32 s0, s0, 0x100
	s_addc_u32 s1, s1, 0
	s_add_u32 s58, s58, 0x100
	s_addc_u32 s59, s59, 0

; #define PG8_STAGE(bufoff, gbase, voff) do { _Pragma("unroll") for (int _i = 0; _i < 2; ++_i) \
;         __builtin_amdgcn_global_load_lds((const unsigned*)((const char*)(gbase) + (voff)[_i]), (PG8_LAS unsigned*)(lds + (bufoff) + ldsw + _i * 8192), 16, 0, 0); } while (0)
; #define PG8_STAGEA(bufoff, gbase, voff) do { _Pragma("unroll") for (int _i = 0; _i < 2; ++_i) \
;         __builtin_amdgcn_global_load_lds((const unsigned*)((const char*)(gbase) + (voff)[_i]), (PG8_LAS unsigned*)(lds + (bufoff) + ldsw + _i * 8192), 16, 0, A_AUX); } while (0)
; #define PG8_LDA(dst, b, h) do { _Pragma("unroll") for (int m = 0; m < 4; ++m) _Pragma("unroll") for (int k = 0; k < 2; ++k) dst[m][k] = *(const PG8_LAS bf16x8*)(lds + PG8_SA(b, h) + aoff + m * 2048 + k * 1024); } while (0)
; #define PG8_LDB(dst, b, h) do { _Pragma("unroll") for (int n = 0; n < 2; ++n) _Pragma("unroll") for (int k = 0; k < 2; ++k) dst[n][k] = *(const PG8_LAS bf16x8*)(lds + PG8_SB(b, h) + boff + n * 2048 + k * 1024); } while (0)
; #define PG8_MMA(ai, bj, At, Bt) do { __builtin_amdgcn_s_setprio(1); _Pragma("unroll") for (int m = 0; m < 4; ++m) _Pragma("unroll") for (int n = 0; n < 2; ++n) _Pragma("unroll") for (int k = 0; k < 2; ++k) \
;         acc[ai][bj][m][n] = __builtin_amdgcn_mfma_f32_16x16x32_bf16(Bt[n][k], At[m][k], acc[ai][bj][m][n], 0, 0, 0); __builtin_amdgcn_s_setprio(0); } while (0)
; #define PG8_WAIT_V(n) asm volatile("s_waitcnt vmcnt(" #n ")" ::: "memory")
; #define PG8_WAIT_L(n) asm volatile("s_waitcnt lgkmcnt(" #n ")" ::: "memory")
; #define PG8_BAR __builtin_amdgcn_s_barrier()
;     ...
; #pragma unroll
;     for (int a = 0; a < 2; ++a)
; #pragma unroll
;         for (int b = 0; b < 2; ++b)
; #pragma unroll
;             for (int m = 0; m < 4; ++m)
; #pragma unroll
;                 for (int n = 0; n < 2; ++n) acc[a][b][m][n] = (f32x4){0.f, 0.f, 0.f, 0.f};
;     ...
;             PG8_LDB(B0, 0, 0); PG8_LDB(B1, 0, 1); PG8_SCHED; PG8_LDA(At, 0, 0); PG8_STAGEA(PG8_SA(1, 1), a1 + hstep, voffA);
;             PG8_WAIT_V(8); PG8_WAIT_L(0); PG8_BAR; PG8_MMA(0, 0, At, B0); PG8_MMA(0, 1, At, B1); PG8_BAR; PG8_SCHED;
;             PG8_LDA(At, 0, 1); PG8_STAGE(PG8_SB(0, 0), b2, voffB); PG8_STAGE(PG8_SB(0, 1), b2 + hstep, voffB); PG8_STAGEA(PG8_SA(0, 0), a2, voffA);
;             PG8_WAIT_V(8); PG8_WAIT_L(0); PG8_BAR; PG8_MMA(1, 0, At, B0); PG8_MMA(1, 1, At, B1); PG8_BAR; PG8_SCHED;
.LBB0_442:
	s_ashr_i32 s43, s42, 31
	s_lshl_b64 s[16:17], s[42:43], 19
	s_add_u32 s44, s24, s16
	s_addc_u32 s45, s25, s17
	s_and_b64 s[16:17], s[38:39], exec
	s_cselect_b32 s16, s45, s49
	s_cselect_b32 s17, s44, s48
	s_ashr_i32 s41, s40, 31
	s_lshl_b64 s[46:47], s[40:41], 19
	s_add_u32 s46, s23, s46
	s_addc_u32 s47, s54, s47
	s_and_b64 s[52:53], s[38:39], exec
	s_cselect_b32 s41, s47, s51
	s_cselect_b32 s43, s46, s50
	s_add_u32 s48, s48, 0x40080
	s_addc_u32 s49, s49, 0
	s_add_u32 s65, s50, 0x100
	s_addc_u32 s72, s51, 0
	s_mov_b32 s73, -2
	s_add_u32 s50, s48, 0xfffc0080
	s_addc_u32 s51, s49, -1
	s_add_i32 s70, 0, 0x10000
	s_cmp_eq_u32 s73, 12
	s_cselect_b32 s53, s16, s51
	s_cselect_b32 s52, s17, s50
	v_add_u32_e32 v140, s70, v143
	s_cselect_b32 s51, s41, s72
	s_cselect_b32 s50, s43, s65
	s_add_i32 s76, 0, 0x14000
	ds_read_b128 v[146:149], v140
	ds_read_b128 v[150:153], v140 offset:1024
	ds_read_b128 v[154:157], v140 offset:2048
	ds_read_b128 v[158:161], v140 offset:3072
	v_add_u32_e32 v140, s76, v143
	ds_read_b128 v[174:177], v140
	ds_read_b128 v[178:181], v140 offset:1024
	ds_read_b128 v[182:185], v140 offset:2048
	ds_read_b128 v[186:189], v140 offset:3072
	v_lshl_add_u64 v[140:141], s[48:49], 0, v[136:137]
	s_add_i32 m0, s56, 0xc000
	ds_read_b128 v[200:203], v145
	ds_read_b128 v[208:211], v145 offset:1024
	ds_read_b128 v[212:215], v145 offset:2048
	ds_read_b128 v[216:219], v145 offset:3072
	ds_read_b128 v[220:223], v145 offset:4096
	ds_read_b128 v[224:227], v145 offset:5120
	ds_read_b128 v[228:231], v145 offset:6144
	ds_read_b128 v[232:235], v145 offset:7168
	global_load_lds_dwordx4 v[140:141], off
	v_lshl_add_u64 v[140:141], s[48:49], 0, v[138:139]
	s_add_i32 m0, s56, 0xe000
	s_nop 0
	global_load_lds_dwordx4 v[140:141], off
	s_waitcnt vmcnt(8)
	s_waitcnt lgkmcnt(0)
	s_barrier
	s_setprio 1
	s_waitcnt lgkmcnt(0)
	v_mfma_f32_16x16x32_bf16 v[126:129], v[146:149], v[200:203], 0
	v_mfma_f32_16x16x32_bf16 v[122:125], v[154:157], v[200:203], 0
	v_mfma_f32_16x16x32_bf16 v[114:117], v[146:149], v[212:215], 0
	v_mfma_f32_16x16x32_bf16 v[106:109], v[154:157], v[212:215], 0
	v_mfma_f32_16x16x32_bf16 v[98:101], v[146:149], v[220:223], 0
	v_mfma_f32_16x16x32_bf16 v[90:93], v[154:157], v[220:223], 0
	v_mfma_f32_16x16x32_bf16 v[82:85], v[146:149], v[228:231], 0
	v_mfma_f32_16x16x32_bf16 v[74:77], v[154:157], v[228:231], 0
	v_mfma_f32_16x16x32_bf16 v[126:129], v[150:153], v[208:211], v[126:129]
	v_mfma_f32_16x16x32_bf16 v[122:125], v[158:161], v[208:211], v[122:125]
	v_mfma_f32_16x16x32_bf16 v[114:117], v[150:153], v[216:219], v[114:117]
	v_mfma_f32_16x16x32_bf16 v[106:109], v[158:161], v[216:219], v[106:109]
	v_mfma_f32_16x16x32_bf16 v[98:101], v[150:153], v[224:227], v[98:101]
	v_mfma_f32_16x16x32_bf16 v[90:93], v[158:161], v[224:227], v[90:93]
	v_mfma_f32_16x16x32_bf16 v[82:85], v[150:153], v[232:235], v[82:85]
	v_mfma_f32_16x16x32_bf16 v[74:77], v[158:161], v[232:235], v[74:77]
	s_setprio 0
	s_setprio 1
	v_mfma_f32_16x16x32_bf16 v[118:121], v[174:177], v[200:203], 0
	v_mfma_f32_16x16x32_bf16 v[110:113], v[182:185], v[200:203], 0
	v_mfma_f32_16x16x32_bf16 v[102:105], v[174:177], v[212:215], 0
	v_mfma_f32_16x16x32_bf16 v[94:97], v[182:185], v[212:215], 0
	v_mfma_f32_16x16x32_bf16 v[86:89], v[174:177], v[220:223], 0
	v_mfma_f32_16x16x32_bf16 v[78:81], v[182:185], v[220:223], 0
	v_mfma_f32_16x16x32_bf16 v[70:73], v[174:177], v[228:231], 0
	v_mfma_f32_16x16x32_bf16 v[66:69], v[182:185], v[228:231], 0
	v_mfma_f32_16x16x32_bf16 v[118:121], v[178:181], v[208:211], v[118:121]
	v_mfma_f32_16x16x32_bf16 v[110:113], v[186:189], v[208:211], v[110:113]
	v_mfma_f32_16x16x32_bf16 v[102:105], v[178:181], v[216:219], v[102:105]
	v_mfma_f32_16x16x32_bf16 v[94:97], v[186:189], v[216:219], v[94:97]
	v_mfma_f32_16x16x32_bf16 v[86:89], v[178:181], v[224:227], v[86:89]
	v_mfma_f32_16x16x32_bf16 v[78:81], v[186:189], v[224:227], v[78:81]
	v_mfma_f32_16x16x32_bf16 v[70:73], v[178:181], v[232:235], v[70:73]
	v_mfma_f32_16x16x32_bf16 v[66:69], v[186:189], v[232:235], v[66:69]
	s_setprio 0
	s_barrier
	s_add_i32 s70, s70, s55
	v_lshl_add_u64 v[140:141], s[50:51], 0, v[0:1]
	s_mov_b32 m0, s70
	ds_read_b128 v[200:203], v145 offset:16384
	ds_read_b128 v[208:211], v145 offset:17408
	ds_read_b128 v[212:215], v145 offset:18432
	ds_read_b128 v[216:219], v145 offset:19456
	ds_read_b128 v[220:223], v145 offset:20480
	ds_read_b128 v[224:227], v145 offset:21504
	ds_read_b128 v[228:231], v145 offset:22528
	ds_read_b128 v[232:235], v145 offset:23552
	global_load_lds_dwordx4 v[140:141], off
	s_add_i32 m0, s70, 0x2000
	s_add_u32 s70, s50, 0x40000
	v_lshl_add_u64 v[190:191], s[50:51], 0, v[130:131]
	s_addc_u32 s71, s51, 0
	s_add_i32 s76, s76, s55
	global_load_lds_dwordx4 v[190:191], off
	v_lshl_add_u64 v[236:237], s[70:71], 0, v[0:1]
	s_mov_b32 m0, s76
	v_lshl_add_u64 v[238:239], s[52:53], 0, v[132:133]
	global_load_lds_dwordx4 v[236:237], off
	v_lshl_add_u64 v[236:237], s[70:71], 0, v[130:131]
	s_add_i32 m0, s76, 0x2000
	s_nop 0
	global_load_lds_dwordx4 v[236:237], off
	v_lshl_add_u64 v[236:237], s[52:53], 0, v[134:135]
	s_mov_b32 m0, s56
	s_nop 0
	global_load_lds_dwordx4 v[236:237], off
	s_mov_b32 m0, s57
	s_nop 0
	global_load_lds_dwordx4 v[238:239], off
	s_waitcnt vmcnt(8)
	s_waitcnt lgkmcnt(0)
	s_barrier
; #define PG8_STAGEA(bufoff, gbase, voff) do { _Pragma("unroll") for (int _i = 0; _i < 2; ++_i) \
;         __builtin_amdgcn_global_load_lds((const unsigned*)((const char*)(gbase) + (voff)[_i]), (PG8_LAS unsigned*)(lds + (bufoff) + ldsw + _i * 8192), 16, 0, A_AUX); } while (0)
; #define PG8_LDA(dst, b, h) do { _Pragma("unroll") for (int m = 0; m < 4; ++m) _Pragma("unroll") for (int k = 0; k < 2; ++k) dst[m][k] = *(const PG8_LAS bf16x8*)(lds + PG8_SA(b, h) + aoff + m * 2048 + k * 1024); } while (0)
; #define PG8_LDB(dst, b, h) do { _Pragma("unroll") for (int n = 0; n < 2; ++n) _Pragma("unroll") for (int k = 0; k < 2; ++k) dst[n][k] = *(const PG8_LAS bf16x8*)(lds + PG8_SB(b, h) + boff + n * 2048 + k * 1024); } while (0)
; #define PG8_MMA(ai, bj, At, Bt) do { __builtin_amdgcn_s_setprio(1); _Pragma("unroll") for (int m = 0; m < 4; ++m) _Pragma("unroll") for (int n = 0; n < 2; ++n) _Pragma("unroll") for (int k = 0; k < 2; ++k) \
;         acc[ai][bj][m][n] = __builtin_amdgcn_mfma_f32_16x16x32_bf16(Bt[n][k], At[m][k], acc[ai][bj][m][n], 0, 0, 0); __builtin_amdgcn_s_setprio(0); } while (0)
; #define PG8_WAIT_V(n) asm volatile("s_waitcnt vmcnt(" #n ")" ::: "memory")
; #define PG8_WAIT_L(n) asm volatile("s_waitcnt lgkmcnt(" #n ")" ::: "memory")
; #define PG8_BAR __builtin_amdgcn_s_barrier()
; #define PG8_SCHED __builtin_amdgcn_sched_barrier(0)
;     ...
;             PG8_WAIT_V(8); PG8_WAIT_L(0); PG8_BAR; PG8_MMA(1, 0, At, B0); PG8_MMA(1, 1, At, B1); PG8_BAR; PG8_SCHED;
;             PG8_LDB(B0, 1, 0); PG8_LDB(B1, 1, 1); PG8_SCHED; PG8_LDA(At, 1, 0); PG8_STAGEA(PG8_SA(0, 1), a2 + hstep, voffA);
;             PG8_WAIT_V(8); PG8_WAIT_L(0); PG8_BAR; PG8_MMA(0, 0, At, B0); PG8_MMA(0, 1, At, B1); PG8_BAR; PG8_SCHED;
	s_setprio 1
	s_waitcnt lgkmcnt(0)
	v_mfma_f32_16x16x32_bf16 v[62:65], v[146:149], v[200:203], 0
	v_mfma_f32_16x16x32_bf16 v[58:61], v[154:157], v[200:203], 0
	v_mfma_f32_16x16x32_bf16 v[50:53], v[146:149], v[212:215], 0
	v_mfma_f32_16x16x32_bf16 v[42:45], v[154:157], v[212:215], 0
	v_mfma_f32_16x16x32_bf16 v[34:37], v[146:149], v[220:223], 0
	v_mfma_f32_16x16x32_bf16 v[26:29], v[154:157], v[220:223], 0
	v_mfma_f32_16x16x32_bf16 v[18:21], v[146:149], v[228:231], 0
	v_mfma_f32_16x16x32_bf16 v[10:13], v[154:157], v[228:231], 0
	v_mfma_f32_16x16x32_bf16 v[62:65], v[150:153], v[208:211], v[62:65]
	v_mfma_f32_16x16x32_bf16 v[58:61], v[158:161], v[208:211], v[58:61]
	v_mfma_f32_16x16x32_bf16 v[50:53], v[150:153], v[216:219], v[50:53]
	v_mfma_f32_16x16x32_bf16 v[42:45], v[158:161], v[216:219], v[42:45]
	v_mfma_f32_16x16x32_bf16 v[34:37], v[150:153], v[224:227], v[34:37]
	v_mfma_f32_16x16x32_bf16 v[26:29], v[158:161], v[224:227], v[26:29]
	v_mfma_f32_16x16x32_bf16 v[18:21], v[150:153], v[232:235], v[18:21]
	v_mfma_f32_16x16x32_bf16 v[10:13], v[158:161], v[232:235], v[10:13]
	s_setprio 0
	s_setprio 1
	v_mfma_f32_16x16x32_bf16 v[54:57], v[174:177], v[200:203], 0
	v_mfma_f32_16x16x32_bf16 v[46:49], v[182:185], v[200:203], 0
	v_mfma_f32_16x16x32_bf16 v[38:41], v[174:177], v[212:215], 0
	v_mfma_f32_16x16x32_bf16 v[30:33], v[182:185], v[212:215], 0
	v_mfma_f32_16x16x32_bf16 v[22:25], v[174:177], v[220:223], 0
	v_mfma_f32_16x16x32_bf16 v[14:17], v[182:185], v[220:223], 0
	v_mfma_f32_16x16x32_bf16 v[6:9], v[174:177], v[228:231], 0
	v_mfma_f32_16x16x32_bf16 v[2:5], v[182:185], v[228:231], 0
	v_mfma_f32_16x16x32_bf16 v[54:57], v[178:181], v[208:211], v[54:57]
	v_mfma_f32_16x16x32_bf16 v[46:49], v[186:189], v[208:211], v[46:49]
	v_mfma_f32_16x16x32_bf16 v[38:41], v[178:181], v[216:219], v[38:41]
	v_mfma_f32_16x16x32_bf16 v[30:33], v[186:189], v[216:219], v[30:33]
	v_mfma_f32_16x16x32_bf16 v[22:25], v[178:181], v[224:227], v[22:25]
	v_mfma_f32_16x16x32_bf16 v[14:17], v[186:189], v[224:227], v[14:17]
	v_mfma_f32_16x16x32_bf16 v[6:9], v[178:181], v[232:235], v[6:9]
	v_mfma_f32_16x16x32_bf16 v[2:5], v[186:189], v[232:235], v[2:5]
	s_setprio 0
	s_barrier
	s_add_i32 s70, 0, 0x18000
	s_add_i32 s71, 0, 0x1c000
	v_add_u32_e32 v158, s70, v143
	v_add_u32_e32 v186, s71, v143
	ds_read_b128 v[146:149], v158
	ds_read_b128 v[150:153], v158 offset:1024
	ds_read_b128 v[154:157], v158 offset:2048
	ds_read_b128 v[158:161], v158 offset:3072
	ds_read_b128 v[174:177], v186
	ds_read_b128 v[178:181], v186 offset:1024
	ds_read_b128 v[182:185], v186 offset:2048
	ds_read_b128 v[186:189], v186 offset:3072
	s_add_u32 s52, s52, 0x40000
	s_addc_u32 s53, s53, 0
	s_mov_b32 m0, s58
	v_lshl_add_u64 v[240:241], s[52:53], 0, v[134:135]
	ds_read_b128 v[200:203], v145 offset:32768
	ds_read_b128 v[208:211], v145 offset:33792
	ds_read_b128 v[212:215], v145 offset:34816
	ds_read_b128 v[216:219], v145 offset:35840
	ds_read_b128 v[220:223], v145 offset:36864
	ds_read_b128 v[224:227], v145 offset:37888
	ds_read_b128 v[228:231], v145 offset:38912
	ds_read_b128 v[232:235], v145 offset:39936
	global_load_lds_dwordx4 v[240:241], off
	v_lshl_add_u64 v[240:241], s[52:53], 0, v[132:133]
	s_mov_b32 m0, s59
	s_nop 0
	global_load_lds_dwordx4 v[240:241], off
	s_waitcnt vmcnt(8)
	s_waitcnt lgkmcnt(0)
	s_barrier
	s_setprio 1
	s_waitcnt lgkmcnt(0)
	v_mfma_f32_16x16x32_bf16 v[126:129], v[146:149], v[200:203], v[126:129]
	v_mfma_f32_16x16x32_bf16 v[122:125], v[154:157], v[200:203], v[122:125]
	v_mfma_f32_16x16x32_bf16 v[114:117], v[146:149], v[212:215], v[114:117]
	v_mfma_f32_16x16x32_bf16 v[106:109], v[154:157], v[212:215], v[106:109]
	v_mfma_f32_16x16x32_bf16 v[98:101], v[146:149], v[220:223], v[98:101]
	v_mfma_f32_16x16x32_bf16 v[90:93], v[154:157], v[220:223], v[90:93]
	v_mfma_f32_16x16x32_bf16 v[82:85], v[146:149], v[228:231], v[82:85]
	v_mfma_f32_16x16x32_bf16 v[74:77], v[154:157], v[228:231], v[74:77]
	v_mfma_f32_16x16x32_bf16 v[126:129], v[150:153], v[208:211], v[126:129]
	v_mfma_f32_16x16x32_bf16 v[122:125], v[158:161], v[208:211], v[122:125]
	v_mfma_f32_16x16x32_bf16 v[114:117], v[150:153], v[216:219], v[114:117]
	v_mfma_f32_16x16x32_bf16 v[106:109], v[158:161], v[216:219], v[106:109]
	v_mfma_f32_16x16x32_bf16 v[98:101], v[150:153], v[224:227], v[98:101]
	v_mfma_f32_16x16x32_bf16 v[90:93], v[158:161], v[224:227], v[90:93]
	v_mfma_f32_16x16x32_bf16 v[82:85], v[150:153], v[232:235], v[82:85]
	v_mfma_f32_16x16x32_bf16 v[74:77], v[158:161], v[232:235], v[74:77]
	s_setprio 0
	s_setprio 1
	v_mfma_f32_16x16x32_bf16 v[118:121], v[174:177], v[200:203], v[118:121]
	v_mfma_f32_16x16x32_bf16 v[110:113], v[182:185], v[200:203], v[110:113]
	v_mfma_f32_16x16x32_bf16 v[102:105], v[174:177], v[212:215], v[102:105]
	v_mfma_f32_16x16x32_bf16 v[94:97], v[182:185], v[212:215], v[94:97]
	v_mfma_f32_16x16x32_bf16 v[86:89], v[174:177], v[220:223], v[86:89]
	v_mfma_f32_16x16x32_bf16 v[78:81], v[182:185], v[220:223], v[78:81]
	v_mfma_f32_16x16x32_bf16 v[70:73], v[174:177], v[228:231], v[70:73]
	v_mfma_f32_16x16x32_bf16 v[66:69], v[182:185], v[228:231], v[66:69]
	v_mfma_f32_16x16x32_bf16 v[118:121], v[178:181], v[208:211], v[118:121]
	v_mfma_f32_16x16x32_bf16 v[110:113], v[186:189], v[208:211], v[110:113]
	v_mfma_f32_16x16x32_bf16 v[102:105], v[178:181], v[216:219], v[102:105]
	v_mfma_f32_16x16x32_bf16 v[94:97], v[186:189], v[216:219], v[94:97]
	v_mfma_f32_16x16x32_bf16 v[86:89], v[178:181], v[224:227], v[86:89]
	v_mfma_f32_16x16x32_bf16 v[78:81], v[186:189], v[224:227], v[78:81]
	v_mfma_f32_16x16x32_bf16 v[70:73], v[178:181], v[232:235], v[70:73]
	v_mfma_f32_16x16x32_bf16 v[66:69], v[186:189], v[232:235], v[66:69]
	s_setprio 0
	s_barrier
; #define PG8_STAGE(bufoff, gbase, voff) do { _Pragma("unroll") for (int _i = 0; _i < 2; ++_i) \
;         __builtin_amdgcn_global_load_lds((const unsigned*)((const char*)(gbase) + (voff)[_i]), (PG8_LAS unsigned*)(lds + (bufoff) + ldsw + _i * 8192), 16, 0, 0); } while (0)
; #define PG8_STAGEA(bufoff, gbase, voff) do { _Pragma("unroll") for (int _i = 0; _i < 2; ++_i) \
;         __builtin_amdgcn_global_load_lds((const unsigned*)((const char*)(gbase) + (voff)[_i]), (PG8_LAS unsigned*)(lds + (bufoff) + ldsw + _i * 8192), 16, 0, A_AUX); } while (0)
; #define PG8_LDA(dst, b, h) do { _Pragma("unroll") for (int m = 0; m < 4; ++m) _Pragma("unroll") for (int k = 0; k < 2; ++k) dst[m][k] = *(const PG8_LAS bf16x8*)(lds + PG8_SA(b, h) + aoff + m * 2048 + k * 1024); } while (0)
; #define PG8_MMA(ai, bj, At, Bt) do { __builtin_amdgcn_s_setprio(1); _Pragma("unroll") for (int m = 0; m < 4; ++m) _Pragma("unroll") for (int n = 0; n < 2; ++n) _Pragma("unroll") for (int k = 0; k < 2; ++k) \
;         acc[ai][bj][m][n] = __builtin_amdgcn_mfma_f32_16x16x32_bf16(Bt[n][k], At[m][k], acc[ai][bj][m][n], 0, 0, 0); __builtin_amdgcn_s_setprio(0); } while (0)
; #define PG8_WAIT_V(n) asm volatile("s_waitcnt vmcnt(" #n ")" ::: "memory")
; #define PG8_WAIT_L(n) asm volatile("s_waitcnt lgkmcnt(" #n ")" ::: "memory")
; #define PG8_BAR __builtin_amdgcn_s_barrier()
; #define PG8_SCHED __builtin_amdgcn_sched_barrier(0)
;     ...
;         for (int t = 0; t < nt; t += 2) {
;     ...
;             PG8_LDA(At, 1, 1); PG8_STAGE(PG8_SB(1, 0), b3, voffB); PG8_STAGE(PG8_SB(1, 1), b3 + hstep, voffB); PG8_STAGEA(PG8_SA(1, 0), a3, voffA);
;             PG8_WAIT_V(8); PG8_WAIT_L(0); PG8_BAR; PG8_MMA(1, 0, At, B0); PG8_MMA(1, 1, At, B1); PG8_BAR; PG8_SCHED;
	s_add_i32 s52, s70, s55
	v_lshl_add_u64 v[140:141], v[140:141], 0, s[8:9]
	s_mov_b32 m0, s52
	ds_read_b128 v[200:203], v145 offset:49152
	ds_read_b128 v[208:211], v145 offset:50176
	ds_read_b128 v[212:215], v145 offset:51200
	ds_read_b128 v[216:219], v145 offset:52224
	ds_read_b128 v[220:223], v145 offset:53248
	ds_read_b128 v[224:227], v145 offset:54272
	ds_read_b128 v[228:231], v145 offset:55296
	ds_read_b128 v[232:235], v145 offset:56320
	global_load_lds_dwordx4 v[140:141], off
	s_add_i32 m0, s52, 0x2000
	s_add_u32 s50, s50, 0x40080
	v_lshl_add_u64 v[140:141], v[190:191], 0, s[8:9]
	s_addc_u32 s51, s51, 0
	s_add_i32 s52, s71, s55
	global_load_lds_dwordx4 v[140:141], off
	v_lshl_add_u64 v[140:141], s[50:51], 0, v[0:1]
	s_mov_b32 m0, s52
	s_nop 0
	global_load_lds_dwordx4 v[140:141], off
	v_lshl_add_u64 v[140:141], s[50:51], 0, v[130:131]
	s_add_i32 m0, s52, 0x2000
	s_nop 0
	global_load_lds_dwordx4 v[140:141], off
	v_lshl_add_u64 v[140:141], v[236:237], 0, s[8:9]
	s_mov_b32 m0, s60
	s_nop 0
	global_load_lds_dwordx4 v[140:141], off
	v_lshl_add_u64 v[140:141], v[238:239], 0, s[8:9]
	s_mov_b32 m0, s61
	s_nop 0
	global_load_lds_dwordx4 v[140:141], off
	s_waitcnt vmcnt(8)
	s_waitcnt lgkmcnt(0)
	s_barrier
	s_setprio 1
	s_waitcnt lgkmcnt(0)
	v_mfma_f32_16x16x32_bf16 v[62:65], v[146:149], v[200:203], v[62:65]
	v_mfma_f32_16x16x32_bf16 v[58:61], v[154:157], v[200:203], v[58:61]
	v_mfma_f32_16x16x32_bf16 v[50:53], v[146:149], v[212:215], v[50:53]
	v_mfma_f32_16x16x32_bf16 v[42:45], v[154:157], v[212:215], v[42:45]
	v_mfma_f32_16x16x32_bf16 v[34:37], v[146:149], v[220:223], v[34:37]
	v_mfma_f32_16x16x32_bf16 v[26:29], v[154:157], v[220:223], v[26:29]
	v_mfma_f32_16x16x32_bf16 v[18:21], v[146:149], v[228:231], v[18:21]
	v_mfma_f32_16x16x32_bf16 v[10:13], v[154:157], v[228:231], v[10:13]
	v_mfma_f32_16x16x32_bf16 v[62:65], v[150:153], v[208:211], v[62:65]
	v_mfma_f32_16x16x32_bf16 v[58:61], v[158:161], v[208:211], v[58:61]
	v_mfma_f32_16x16x32_bf16 v[50:53], v[150:153], v[216:219], v[50:53]
	v_mfma_f32_16x16x32_bf16 v[42:45], v[158:161], v[216:219], v[42:45]
	v_mfma_f32_16x16x32_bf16 v[34:37], v[150:153], v[224:227], v[34:37]
	v_mfma_f32_16x16x32_bf16 v[26:29], v[158:161], v[224:227], v[26:29]
	v_mfma_f32_16x16x32_bf16 v[18:21], v[150:153], v[232:235], v[18:21]
	v_mfma_f32_16x16x32_bf16 v[10:13], v[158:161], v[232:235], v[10:13]
	s_setprio 0
	s_setprio 1
	v_mfma_f32_16x16x32_bf16 v[54:57], v[174:177], v[200:203], v[54:57]
	v_mfma_f32_16x16x32_bf16 v[46:49], v[182:185], v[200:203], v[46:49]
	v_mfma_f32_16x16x32_bf16 v[38:41], v[174:177], v[212:215], v[38:41]
	v_mfma_f32_16x16x32_bf16 v[30:33], v[182:185], v[212:215], v[30:33]
	v_mfma_f32_16x16x32_bf16 v[22:25], v[174:177], v[220:223], v[22:25]
	v_mfma_f32_16x16x32_bf16 v[14:17], v[182:185], v[220:223], v[14:17]
	v_mfma_f32_16x16x32_bf16 v[6:9], v[174:177], v[228:231], v[6:9]
	v_mfma_f32_16x16x32_bf16 v[2:5], v[182:185], v[228:231], v[2:5]
	v_mfma_f32_16x16x32_bf16 v[54:57], v[178:181], v[208:211], v[54:57]
	v_mfma_f32_16x16x32_bf16 v[46:49], v[186:189], v[208:211], v[46:49]
	v_mfma_f32_16x16x32_bf16 v[38:41], v[178:181], v[216:219], v[38:41]
	v_mfma_f32_16x16x32_bf16 v[30:33], v[186:189], v[216:219], v[30:33]
	v_mfma_f32_16x16x32_bf16 v[22:25], v[178:181], v[224:227], v[22:25]
	v_mfma_f32_16x16x32_bf16 v[14:17], v[186:189], v[224:227], v[14:17]
	v_mfma_f32_16x16x32_bf16 v[6:9], v[178:181], v[232:235], v[6:9]
	v_mfma_f32_16x16x32_bf16 v[2:5], v[186:189], v[232:235], v[2:5]
	s_setprio 0
	s_barrier
	s_add_i32 s73, s73, 2
	s_add_u32 s48, s48, 0x100
	s_addc_u32 s49, s49, 0
	s_add_u32 s65, s65, 0x100
	s_addc_u32 s72, s72, 0

; #define PG8_STAGE(bufoff, gbase, voff) do { _Pragma("unroll") for (int _i = 0; _i < 2; ++_i) \
;         __builtin_amdgcn_global_load_lds((const unsigned*)((const char*)(gbase) + (voff)[_i]), (PG8_LAS unsigned*)(lds + (bufoff) + ldsw + _i * 8192), 16, 0, 0); } while (0)
; #define PG8_STAGEA(bufoff, gbase, voff) do { _Pragma("unroll") for (int _i = 0; _i < 2; ++_i) \
;         __builtin_amdgcn_global_load_lds((const unsigned*)((const char*)(gbase) + (voff)[_i]), (PG8_LAS unsigned*)(lds + (bufoff) + ldsw + _i * 8192), 16, 0, A_AUX); } while (0)
; #define PG8_LDA(dst, b, h) do { _Pragma("unroll") for (int m = 0; m < 4; ++m) _Pragma("unroll") for (int k = 0; k < 2; ++k) dst[m][k] = *(const PG8_LAS bf16x8*)(lds + PG8_SA(b, h) + aoff + m * 2048 + k * 1024); } while (0)
; #define PG8_LDB(dst, b, h) do { _Pragma("unroll") for (int n = 0; n < 2; ++n) _Pragma("unroll") for (int k = 0; k < 2; ++k) dst[n][k] = *(const PG8_LAS bf16x8*)(lds + PG8_SB(b, h) + boff + n * 2048 + k * 1024); } while (0)
; #define PG8_MMA(ai, bj, At, Bt) do { __builtin_amdgcn_s_setprio(1); _Pragma("unroll") for (int m = 0; m < 4; ++m) _Pragma("unroll") for (int n = 0; n < 2; ++n) _Pragma("unroll") for (int k = 0; k < 2; ++k) \
;         acc[ai][bj][m][n] = __builtin_amdgcn_mfma_f32_16x16x32_bf16(Bt[n][k], At[m][k], acc[ai][bj][m][n], 0, 0, 0); __builtin_amdgcn_s_setprio(0); } while (0)
; #define PG8_WAIT_V(n) asm volatile("s_waitcnt vmcnt(" #n ")" ::: "memory")
; #define PG8_WAIT_L(n) asm volatile("s_waitcnt lgkmcnt(" #n ")" ::: "memory")
; #define PG8_BAR __builtin_amdgcn_s_barrier()
;     ...
; #pragma unroll
;     for (int a = 0; a < 2; ++a)
; #pragma unroll
;         for (int b = 0; b < 2; ++b)
; #pragma unroll
;             for (int m = 0; m < 4; ++m)
; #pragma unroll
;                 for (int n = 0; n < 2; ++n) acc[a][b][m][n] = (f32x4){0.f, 0.f, 0.f, 0.f};
;     ...
;             PG8_LDB(B0, 0, 0); PG8_LDB(B1, 0, 1); PG8_SCHED; PG8_LDA(At, 0, 0); PG8_STAGEA(PG8_SA(1, 1), a1 + hstep, voffA);
;             PG8_WAIT_V(8); PG8_WAIT_L(0); PG8_BAR; PG8_MMA(0, 0, At, B0); PG8_MMA(0, 1, At, B1); PG8_BAR; PG8_SCHED;
;             PG8_LDA(At, 0, 1); PG8_STAGE(PG8_SB(0, 0), b2, voffB); PG8_STAGE(PG8_SB(0, 1), b2 + hstep, voffB); PG8_STAGEA(PG8_SA(0, 0), a2, voffA);
;             PG8_WAIT_V(8); PG8_WAIT_L(0); PG8_BAR; PG8_MMA(1, 0, At, B0); PG8_MMA(1, 1, At, B1); PG8_BAR; PG8_SCHED;
.LBB0_655:
	s_add_u32 s16, s48, 0x100
	s_addc_u32 s17, s49, 0
	s_mov_b32 s73, -2
	s_add_u32 s48, s46, 0x100
	s_addc_u32 s49, s47, 0
	s_add_i32 s70, 0, 0x10000
	s_cmp_eq_u32 s73, 40
	s_cselect_b32 s53, s1, s49
	s_cselect_b32 s52, s0, s48
	v_add_u32_e32 v140, s70, v143
	s_cselect_b32 s51, s45, s17
	s_cselect_b32 s50, s44, s16
	s_add_i32 s71, 0, 0x14000
	ds_read_b128 v[146:149], v140
	ds_read_b128 v[150:153], v140 offset:1024
	ds_read_b128 v[154:157], v140 offset:2048
	ds_read_b128 v[158:161], v140 offset:3072
	v_add_u32_e32 v140, s71, v143
	ds_read_b128 v[174:177], v140
	ds_read_b128 v[178:181], v140 offset:1024
	ds_read_b128 v[182:185], v140 offset:2048
	ds_read_b128 v[186:189], v140 offset:3072
	v_lshl_add_u64 v[140:141], s[46:47], 0, v[136:137]
	s_add_i32 m0, s56, 0xc000
	ds_read_b128 v[200:203], v145
	ds_read_b128 v[208:211], v145 offset:1024
	ds_read_b128 v[212:215], v145 offset:2048
	ds_read_b128 v[216:219], v145 offset:3072
	ds_read_b128 v[220:223], v145 offset:4096
	ds_read_b128 v[224:227], v145 offset:5120
	ds_read_b128 v[228:231], v145 offset:6144
	ds_read_b128 v[232:235], v145 offset:7168
	global_load_lds_dwordx4 v[140:141], off
	v_lshl_add_u64 v[140:141], s[46:47], 0, v[138:139]
	s_add_i32 m0, s56, 0xe000
	s_nop 0
	global_load_lds_dwordx4 v[140:141], off
	s_waitcnt vmcnt(8)
	s_waitcnt lgkmcnt(0)
	s_barrier
	s_setprio 1
	s_waitcnt lgkmcnt(0)
	v_mfma_f32_16x16x32_bf16 v[126:129], v[146:149], v[200:203], 0
	v_mfma_f32_16x16x32_bf16 v[122:125], v[154:157], v[200:203], 0
	v_mfma_f32_16x16x32_bf16 v[114:117], v[146:149], v[212:215], 0
	v_mfma_f32_16x16x32_bf16 v[106:109], v[154:157], v[212:215], 0
	v_mfma_f32_16x16x32_bf16 v[98:101], v[146:149], v[220:223], 0
	v_mfma_f32_16x16x32_bf16 v[90:93], v[154:157], v[220:223], 0
	v_mfma_f32_16x16x32_bf16 v[82:85], v[146:149], v[228:231], 0
	v_mfma_f32_16x16x32_bf16 v[74:77], v[154:157], v[228:231], 0
	v_mfma_f32_16x16x32_bf16 v[126:129], v[150:153], v[208:211], v[126:129]
	v_mfma_f32_16x16x32_bf16 v[122:125], v[158:161], v[208:211], v[122:125]
	v_mfma_f32_16x16x32_bf16 v[114:117], v[150:153], v[216:219], v[114:117]
	v_mfma_f32_16x16x32_bf16 v[106:109], v[158:161], v[216:219], v[106:109]
	v_mfma_f32_16x16x32_bf16 v[98:101], v[150:153], v[224:227], v[98:101]
	v_mfma_f32_16x16x32_bf16 v[90:93], v[158:161], v[224:227], v[90:93]
	v_mfma_f32_16x16x32_bf16 v[82:85], v[150:153], v[232:235], v[82:85]
	v_mfma_f32_16x16x32_bf16 v[74:77], v[158:161], v[232:235], v[74:77]
	s_setprio 0
	s_setprio 1
	v_mfma_f32_16x16x32_bf16 v[118:121], v[174:177], v[200:203], 0
	v_mfma_f32_16x16x32_bf16 v[110:113], v[182:185], v[200:203], 0
	v_mfma_f32_16x16x32_bf16 v[102:105], v[174:177], v[212:215], 0
	v_mfma_f32_16x16x32_bf16 v[94:97], v[182:185], v[212:215], 0
	v_mfma_f32_16x16x32_bf16 v[86:89], v[174:177], v[220:223], 0
	v_mfma_f32_16x16x32_bf16 v[78:81], v[182:185], v[220:223], 0
	v_mfma_f32_16x16x32_bf16 v[70:73], v[174:177], v[228:231], 0
	v_mfma_f32_16x16x32_bf16 v[66:69], v[182:185], v[228:231], 0
	v_mfma_f32_16x16x32_bf16 v[118:121], v[178:181], v[208:211], v[118:121]
	v_mfma_f32_16x16x32_bf16 v[110:113], v[186:189], v[208:211], v[110:113]
	v_mfma_f32_16x16x32_bf16 v[102:105], v[178:181], v[216:219], v[102:105]
	v_mfma_f32_16x16x32_bf16 v[94:97], v[186:189], v[216:219], v[94:97]
	v_mfma_f32_16x16x32_bf16 v[86:89], v[178:181], v[224:227], v[86:89]
	v_mfma_f32_16x16x32_bf16 v[78:81], v[186:189], v[224:227], v[78:81]
	v_mfma_f32_16x16x32_bf16 v[70:73], v[178:181], v[232:235], v[70:73]
	v_mfma_f32_16x16x32_bf16 v[66:69], v[186:189], v[232:235], v[66:69]
	s_setprio 0
	s_barrier
	s_add_i32 s46, s70, s55
	v_lshl_add_u64 v[140:141], s[50:51], 0, v[0:1]
	s_mov_b32 m0, s46
	ds_read_b128 v[200:203], v145 offset:16384
	ds_read_b128 v[208:211], v145 offset:17408
	ds_read_b128 v[212:215], v145 offset:18432
	ds_read_b128 v[216:219], v145 offset:19456
	ds_read_b128 v[220:223], v145 offset:20480
	ds_read_b128 v[224:227], v145 offset:21504
	ds_read_b128 v[228:231], v145 offset:22528
	ds_read_b128 v[232:235], v145 offset:23552
	global_load_lds_dwordx4 v[140:141], off
	s_add_i32 m0, s46, 0x2000
	s_add_u32 s46, s50, 0xb0000
	v_lshl_add_u64 v[190:191], s[50:51], 0, v[130:131]
	s_addc_u32 s47, s51, 0
	s_add_i32 s70, s71, s55
	global_load_lds_dwordx4 v[190:191], off
	v_lshl_add_u64 v[236:237], s[46:47], 0, v[0:1]
	s_mov_b32 m0, s70
	v_lshl_add_u64 v[238:239], s[52:53], 0, v[132:133]
	global_load_lds_dwordx4 v[236:237], off
	v_lshl_add_u64 v[236:237], s[46:47], 0, v[130:131]
	s_add_i32 m0, s70, 0x2000
	s_nop 0
	global_load_lds_dwordx4 v[236:237], off
	v_lshl_add_u64 v[236:237], s[52:53], 0, v[134:135]
	s_mov_b32 m0, s56
	s_nop 0
	global_load_lds_dwordx4 v[236:237], off
	s_mov_b32 m0, s57
	s_nop 0
	global_load_lds_dwordx4 v[238:239], off
	s_waitcnt vmcnt(8)
	s_waitcnt lgkmcnt(0)
	s_barrier
; #define PG8_STAGEA(bufoff, gbase, voff) do { _Pragma("unroll") for (int _i = 0; _i < 2; ++_i) \
;         __builtin_amdgcn_global_load_lds((const unsigned*)((const char*)(gbase) + (voff)[_i]), (PG8_LAS unsigned*)(lds + (bufoff) + ldsw + _i * 8192), 16, 0, A_AUX); } while (0)
; #define PG8_LDA(dst, b, h) do { _Pragma("unroll") for (int m = 0; m < 4; ++m) _Pragma("unroll") for (int k = 0; k < 2; ++k) dst[m][k] = *(const PG8_LAS bf16x8*)(lds + PG8_SA(b, h) + aoff + m * 2048 + k * 1024); } while (0)
; #define PG8_LDB(dst, b, h) do { _Pragma("unroll") for (int n = 0; n < 2; ++n) _Pragma("unroll") for (int k = 0; k < 2; ++k) dst[n][k] = *(const PG8_LAS bf16x8*)(lds + PG8_SB(b, h) + boff + n * 2048 + k * 1024); } while (0)
; #define PG8_MMA(ai, bj, At, Bt) do { __builtin_amdgcn_s_setprio(1); _Pragma("unroll") for (int m = 0; m < 4; ++m) _Pragma("unroll") for (int n = 0; n < 2; ++n) _Pragma("unroll") for (int k = 0; k < 2; ++k) \
;         acc[ai][bj][m][n] = __builtin_amdgcn_mfma_f32_16x16x32_bf16(Bt[n][k], At[m][k], acc[ai][bj][m][n], 0, 0, 0); __builtin_amdgcn_s_setprio(0); } while (0)
; #define PG8_WAIT_V(n) asm volatile("s_waitcnt vmcnt(" #n ")" ::: "memory")
; #define PG8_WAIT_L(n) asm volatile("s_waitcnt lgkmcnt(" #n ")" ::: "memory")
; #define PG8_BAR __builtin_amdgcn_s_barrier()
; #define PG8_SCHED __builtin_amdgcn_sched_barrier(0)
;     ...
;             PG8_WAIT_V(8); PG8_WAIT_L(0); PG8_BAR; PG8_MMA(1, 0, At, B0); PG8_MMA(1, 1, At, B1); PG8_BAR; PG8_SCHED;
;             PG8_LDB(B0, 1, 0); PG8_LDB(B1, 1, 1); PG8_SCHED; PG8_LDA(At, 1, 0); PG8_STAGEA(PG8_SA(0, 1), a2 + hstep, voffA);
;             PG8_WAIT_V(8); PG8_WAIT_L(0); PG8_BAR; PG8_MMA(0, 0, At, B0); PG8_MMA(0, 1, At, B1); PG8_BAR; PG8_SCHED;
	s_setprio 1
	s_waitcnt lgkmcnt(0)
	v_mfma_f32_16x16x32_bf16 v[62:65], v[146:149], v[200:203], 0
	v_mfma_f32_16x16x32_bf16 v[58:61], v[154:157], v[200:203], 0
	v_mfma_f32_16x16x32_bf16 v[50:53], v[146:149], v[212:215], 0
	v_mfma_f32_16x16x32_bf16 v[42:45], v[154:157], v[212:215], 0
	v_mfma_f32_16x16x32_bf16 v[34:37], v[146:149], v[220:223], 0
	v_mfma_f32_16x16x32_bf16 v[26:29], v[154:157], v[220:223], 0
	v_mfma_f32_16x16x32_bf16 v[18:21], v[146:149], v[228:231], 0
	v_mfma_f32_16x16x32_bf16 v[10:13], v[154:157], v[228:231], 0
	v_mfma_f32_16x16x32_bf16 v[62:65], v[150:153], v[208:211], v[62:65]
	v_mfma_f32_16x16x32_bf16 v[58:61], v[158:161], v[208:211], v[58:61]
	v_mfma_f32_16x16x32_bf16 v[50:53], v[150:153], v[216:219], v[50:53]
	v_mfma_f32_16x16x32_bf16 v[42:45], v[158:161], v[216:219], v[42:45]
	v_mfma_f32_16x16x32_bf16 v[34:37], v[150:153], v[224:227], v[34:37]
	v_mfma_f32_16x16x32_bf16 v[26:29], v[158:161], v[224:227], v[26:29]
	v_mfma_f32_16x16x32_bf16 v[18:21], v[150:153], v[232:235], v[18:21]
	v_mfma_f32_16x16x32_bf16 v[10:13], v[158:161], v[232:235], v[10:13]
	s_setprio 0
	s_setprio 1
	v_mfma_f32_16x16x32_bf16 v[54:57], v[174:177], v[200:203], 0
	v_mfma_f32_16x16x32_bf16 v[46:49], v[182:185], v[200:203], 0
	v_mfma_f32_16x16x32_bf16 v[38:41], v[174:177], v[212:215], 0
	v_mfma_f32_16x16x32_bf16 v[30:33], v[182:185], v[212:215], 0
	v_mfma_f32_16x16x32_bf16 v[22:25], v[174:177], v[220:223], 0
	v_mfma_f32_16x16x32_bf16 v[14:17], v[182:185], v[220:223], 0
	v_mfma_f32_16x16x32_bf16 v[6:9], v[174:177], v[228:231], 0
	v_mfma_f32_16x16x32_bf16 v[2:5], v[182:185], v[228:231], 0
	v_mfma_f32_16x16x32_bf16 v[54:57], v[178:181], v[208:211], v[54:57]
	v_mfma_f32_16x16x32_bf16 v[46:49], v[186:189], v[208:211], v[46:49]
	v_mfma_f32_16x16x32_bf16 v[38:41], v[178:181], v[216:219], v[38:41]
	v_mfma_f32_16x16x32_bf16 v[30:33], v[186:189], v[216:219], v[30:33]
	v_mfma_f32_16x16x32_bf16 v[22:25], v[178:181], v[224:227], v[22:25]
	v_mfma_f32_16x16x32_bf16 v[14:17], v[186:189], v[224:227], v[14:17]
	v_mfma_f32_16x16x32_bf16 v[6:9], v[178:181], v[232:235], v[6:9]
	v_mfma_f32_16x16x32_bf16 v[2:5], v[186:189], v[232:235], v[2:5]
	s_setprio 0
	s_barrier
	s_add_i32 s70, 0, 0x18000
	s_add_i32 s71, 0, 0x1c000
	v_add_u32_e32 v158, s70, v143
	v_add_u32_e32 v186, s71, v143
	ds_read_b128 v[146:149], v158
	ds_read_b128 v[150:153], v158 offset:1024
	ds_read_b128 v[154:157], v158 offset:2048
	ds_read_b128 v[158:161], v158 offset:3072
	ds_read_b128 v[174:177], v186
	ds_read_b128 v[178:181], v186 offset:1024
	ds_read_b128 v[182:185], v186 offset:2048
	ds_read_b128 v[186:189], v186 offset:3072
	s_add_u32 s46, s52, 0xb0000
	s_addc_u32 s47, s53, 0
	s_mov_b32 m0, s58
	v_lshl_add_u64 v[240:241], s[46:47], 0, v[134:135]
	ds_read_b128 v[200:203], v145 offset:32768
	ds_read_b128 v[208:211], v145 offset:33792
	ds_read_b128 v[212:215], v145 offset:34816
	ds_read_b128 v[216:219], v145 offset:35840
	ds_read_b128 v[220:223], v145 offset:36864
	ds_read_b128 v[224:227], v145 offset:37888
	ds_read_b128 v[228:231], v145 offset:38912
	ds_read_b128 v[232:235], v145 offset:39936
	global_load_lds_dwordx4 v[240:241], off
	v_lshl_add_u64 v[240:241], s[46:47], 0, v[132:133]
	s_mov_b32 m0, s59
	s_nop 0
	global_load_lds_dwordx4 v[240:241], off
	s_waitcnt vmcnt(8)
	s_waitcnt lgkmcnt(0)
	s_barrier
	s_setprio 1
	s_waitcnt lgkmcnt(0)
	v_mfma_f32_16x16x32_bf16 v[126:129], v[146:149], v[200:203], v[126:129]
	v_mfma_f32_16x16x32_bf16 v[122:125], v[154:157], v[200:203], v[122:125]
	v_mfma_f32_16x16x32_bf16 v[114:117], v[146:149], v[212:215], v[114:117]
	v_mfma_f32_16x16x32_bf16 v[106:109], v[154:157], v[212:215], v[106:109]
	v_mfma_f32_16x16x32_bf16 v[98:101], v[146:149], v[220:223], v[98:101]
	v_mfma_f32_16x16x32_bf16 v[90:93], v[154:157], v[220:223], v[90:93]
	v_mfma_f32_16x16x32_bf16 v[82:85], v[146:149], v[228:231], v[82:85]
	v_mfma_f32_16x16x32_bf16 v[74:77], v[154:157], v[228:231], v[74:77]
	v_mfma_f32_16x16x32_bf16 v[126:129], v[150:153], v[208:211], v[126:129]
	v_mfma_f32_16x16x32_bf16 v[122:125], v[158:161], v[208:211], v[122:125]
	v_mfma_f32_16x16x32_bf16 v[114:117], v[150:153], v[216:219], v[114:117]
	v_mfma_f32_16x16x32_bf16 v[106:109], v[158:161], v[216:219], v[106:109]
	v_mfma_f32_16x16x32_bf16 v[98:101], v[150:153], v[224:227], v[98:101]
	v_mfma_f32_16x16x32_bf16 v[90:93], v[158:161], v[224:227], v[90:93]
	v_mfma_f32_16x16x32_bf16 v[82:85], v[150:153], v[232:235], v[82:85]
	v_mfma_f32_16x16x32_bf16 v[74:77], v[158:161], v[232:235], v[74:77]
	s_setprio 0
	s_setprio 1
	v_mfma_f32_16x16x32_bf16 v[118:121], v[174:177], v[200:203], v[118:121]
	v_mfma_f32_16x16x32_bf16 v[110:113], v[182:185], v[200:203], v[110:113]
	v_mfma_f32_16x16x32_bf16 v[102:105], v[174:177], v[212:215], v[102:105]
	v_mfma_f32_16x16x32_bf16 v[94:97], v[182:185], v[212:215], v[94:97]
	v_mfma_f32_16x16x32_bf16 v[86:89], v[174:177], v[220:223], v[86:89]
	v_mfma_f32_16x16x32_bf16 v[78:81], v[182:185], v[220:223], v[78:81]
	v_mfma_f32_16x16x32_bf16 v[70:73], v[174:177], v[228:231], v[70:73]
	v_mfma_f32_16x16x32_bf16 v[66:69], v[182:185], v[228:231], v[66:69]
	v_mfma_f32_16x16x32_bf16 v[118:121], v[178:181], v[208:211], v[118:121]
	v_mfma_f32_16x16x32_bf16 v[110:113], v[186:189], v[208:211], v[110:113]
	v_mfma_f32_16x16x32_bf16 v[102:105], v[178:181], v[216:219], v[102:105]
	v_mfma_f32_16x16x32_bf16 v[94:97], v[186:189], v[216:219], v[94:97]
	v_mfma_f32_16x16x32_bf16 v[86:89], v[178:181], v[224:227], v[86:89]
	v_mfma_f32_16x16x32_bf16 v[78:81], v[186:189], v[224:227], v[78:81]
	v_mfma_f32_16x16x32_bf16 v[70:73], v[178:181], v[232:235], v[70:73]
	v_mfma_f32_16x16x32_bf16 v[66:69], v[186:189], v[232:235], v[66:69]
	s_setprio 0
	s_barrier
; #define PG8_STAGE(bufoff, gbase, voff) do { _Pragma("unroll") for (int _i = 0; _i < 2; ++_i) \
;         __builtin_amdgcn_global_load_lds((const unsigned*)((const char*)(gbase) + (voff)[_i]), (PG8_LAS unsigned*)(lds + (bufoff) + ldsw + _i * 8192), 16, 0, 0); } while (0)
; #define PG8_STAGEA(bufoff, gbase, voff) do { _Pragma("unroll") for (int _i = 0; _i < 2; ++_i) \
;         __builtin_amdgcn_global_load_lds((const unsigned*)((const char*)(gbase) + (voff)[_i]), (PG8_LAS unsigned*)(lds + (bufoff) + ldsw + _i * 8192), 16, 0, A_AUX); } while (0)
; #define PG8_LDA(dst, b, h) do { _Pragma("unroll") for (int m = 0; m < 4; ++m) _Pragma("unroll") for (int k = 0; k < 2; ++k) dst[m][k] = *(const PG8_LAS bf16x8*)(lds + PG8_SA(b, h) + aoff + m * 2048 + k * 1024); } while (0)
; #define PG8_MMA(ai, bj, At, Bt) do { __builtin_amdgcn_s_setprio(1); _Pragma("unroll") for (int m = 0; m < 4; ++m) _Pragma("unroll") for (int n = 0; n < 2; ++n) _Pragma("unroll") for (int k = 0; k < 2; ++k) \
;         acc[ai][bj][m][n] = __builtin_amdgcn_mfma_f32_16x16x32_bf16(Bt[n][k], At[m][k], acc[ai][bj][m][n], 0, 0, 0); __builtin_amdgcn_s_setprio(0); } while (0)
; #define PG8_WAIT_V(n) asm volatile("s_waitcnt vmcnt(" #n ")" ::: "memory")
; #define PG8_WAIT_L(n) asm volatile("s_waitcnt lgkmcnt(" #n ")" ::: "memory")
; #define PG8_BAR __builtin_amdgcn_s_barrier()
; #define PG8_SCHED __builtin_amdgcn_sched_barrier(0)
;     ...
;         for (int t = 0; t < nt; t += 2) {
;     ...
;             PG8_LDA(At, 1, 1); PG8_STAGE(PG8_SB(1, 0), b3, voffB); PG8_STAGE(PG8_SB(1, 1), b3 + hstep, voffB); PG8_STAGEA(PG8_SA(1, 0), a3, voffA);
;             PG8_WAIT_V(8); PG8_WAIT_L(0); PG8_BAR; PG8_MMA(1, 0, At, B0); PG8_MMA(1, 1, At, B1); PG8_BAR; PG8_SCHED;
	s_add_i32 s46, s70, s55
	v_lshl_add_u64 v[140:141], v[140:141], 0, s[8:9]
	s_mov_b32 m0, s46
	ds_read_b128 v[200:203], v145 offset:49152
	ds_read_b128 v[208:211], v145 offset:50176
	ds_read_b128 v[212:215], v145 offset:51200
	ds_read_b128 v[216:219], v145 offset:52224
	ds_read_b128 v[220:223], v145 offset:53248
	ds_read_b128 v[224:227], v145 offset:54272
	ds_read_b128 v[228:231], v145 offset:55296
	ds_read_b128 v[232:235], v145 offset:56320
	global_load_lds_dwordx4 v[140:141], off
	s_add_i32 m0, s46, 0x2000
	s_add_u32 s46, s50, 0xb0080
	v_lshl_add_u64 v[140:141], v[190:191], 0, s[8:9]
	s_addc_u32 s47, s51, 0
	s_add_i32 s50, s71, s55
	global_load_lds_dwordx4 v[140:141], off
	v_lshl_add_u64 v[140:141], s[46:47], 0, v[0:1]
	s_mov_b32 m0, s50
	s_nop 0
	global_load_lds_dwordx4 v[140:141], off
	v_lshl_add_u64 v[140:141], s[46:47], 0, v[130:131]
	s_add_i32 m0, s50, 0x2000
	s_nop 0
	global_load_lds_dwordx4 v[140:141], off
	v_lshl_add_u64 v[140:141], v[236:237], 0, s[8:9]
	s_mov_b32 m0, s60
	s_nop 0
	global_load_lds_dwordx4 v[140:141], off
	v_lshl_add_u64 v[140:141], v[238:239], 0, s[8:9]
	s_mov_b32 m0, s61
	s_nop 0
	global_load_lds_dwordx4 v[140:141], off
	s_waitcnt vmcnt(8)
	s_waitcnt lgkmcnt(0)
	s_barrier
	s_setprio 1
	s_waitcnt lgkmcnt(0)
	v_mfma_f32_16x16x32_bf16 v[62:65], v[146:149], v[200:203], v[62:65]
	v_mfma_f32_16x16x32_bf16 v[58:61], v[154:157], v[200:203], v[58:61]
	v_mfma_f32_16x16x32_bf16 v[50:53], v[146:149], v[212:215], v[50:53]
	v_mfma_f32_16x16x32_bf16 v[42:45], v[154:157], v[212:215], v[42:45]
	v_mfma_f32_16x16x32_bf16 v[34:37], v[146:149], v[220:223], v[34:37]
	v_mfma_f32_16x16x32_bf16 v[26:29], v[154:157], v[220:223], v[26:29]
	v_mfma_f32_16x16x32_bf16 v[18:21], v[146:149], v[228:231], v[18:21]
	v_mfma_f32_16x16x32_bf16 v[10:13], v[154:157], v[228:231], v[10:13]
	v_mfma_f32_16x16x32_bf16 v[62:65], v[150:153], v[208:211], v[62:65]
	v_mfma_f32_16x16x32_bf16 v[58:61], v[158:161], v[208:211], v[58:61]
	v_mfma_f32_16x16x32_bf16 v[50:53], v[150:153], v[216:219], v[50:53]
	v_mfma_f32_16x16x32_bf16 v[42:45], v[158:161], v[216:219], v[42:45]
	v_mfma_f32_16x16x32_bf16 v[34:37], v[150:153], v[224:227], v[34:37]
	v_mfma_f32_16x16x32_bf16 v[26:29], v[158:161], v[224:227], v[26:29]
	v_mfma_f32_16x16x32_bf16 v[18:21], v[150:153], v[232:235], v[18:21]
	v_mfma_f32_16x16x32_bf16 v[10:13], v[158:161], v[232:235], v[10:13]
	s_setprio 0
	s_setprio 1
	v_mfma_f32_16x16x32_bf16 v[54:57], v[174:177], v[200:203], v[54:57]
	v_mfma_f32_16x16x32_bf16 v[46:49], v[182:185], v[200:203], v[46:49]
	v_mfma_f32_16x16x32_bf16 v[38:41], v[174:177], v[212:215], v[38:41]
	v_mfma_f32_16x16x32_bf16 v[30:33], v[182:185], v[212:215], v[30:33]
	v_mfma_f32_16x16x32_bf16 v[22:25], v[174:177], v[220:223], v[22:25]
	v_mfma_f32_16x16x32_bf16 v[14:17], v[182:185], v[220:223], v[14:17]
	v_mfma_f32_16x16x32_bf16 v[6:9], v[174:177], v[228:231], v[6:9]
	v_mfma_f32_16x16x32_bf16 v[2:5], v[182:185], v[228:231], v[2:5]
	v_mfma_f32_16x16x32_bf16 v[54:57], v[178:181], v[208:211], v[54:57]
	v_mfma_f32_16x16x32_bf16 v[46:49], v[186:189], v[208:211], v[46:49]
	v_mfma_f32_16x16x32_bf16 v[38:41], v[178:181], v[216:219], v[38:41]
	v_mfma_f32_16x16x32_bf16 v[30:33], v[186:189], v[216:219], v[30:33]
	v_mfma_f32_16x16x32_bf16 v[22:25], v[178:181], v[224:227], v[22:25]
	v_mfma_f32_16x16x32_bf16 v[14:17], v[186:189], v[224:227], v[14:17]
	v_mfma_f32_16x16x32_bf16 v[6:9], v[178:181], v[232:235], v[6:9]
	v_mfma_f32_16x16x32_bf16 v[2:5], v[186:189], v[232:235], v[2:5]
	s_setprio 0
	s_barrier
	s_add_i32 s73, s73, 2
	s_add_u32 s16, s16, 0x100
	s_addc_u32 s17, s17, 0
	s_cmp_gt_u32 s73, 41
	s_mov_b64 s[46:47], s[48:49]
